# grid barrier: the workgroup that arrives with eight of its XCD still to come starts an extra asynchronous L2 write-back
# baseline (speedup 1.0000x reference)
; __device__ __forceinline__ unsigned xb_ld(unsigned* p)              { return __hip_atomic_load(p, __ATOMIC_RELAXED, __HIP_MEMORY_SCOPE_AGENT); }
; __device__ __forceinline__ unsigned xb_add(unsigned* p, unsigned v) { return __hip_atomic_fetch_add(p, v, __ATOMIC_RELAXED, __HIP_MEMORY_SCOPE_AGENT); }
; #define XB_SPIN(cond, bar) do { unsigned _sp = 0; while (cond) { __builtin_amdgcn_s_sleep(1); \
;     if ((++_sp & 255u) == 0u) { if (xb_ld(&(bar)[XB_TMO])) break; if (_sp > XB_SPIN_CAP) { atomicAdd(&(bar)[XB_TMO], 1u); break; } } } } while (0)
; __device__ __forceinline__ void xcd_barrier(const XcdBarrier& b) {
;     ...
;         unsigned nloc = b.st[0], nx = b.st[1];
;         if (nloc == 0u) { xcd_barrier_complete(bar, b.x, nloc, nx); b.st[0] = nloc; b.st[1] = nx; }
;         const unsigned old = xb_add(&bar[XB_XSUB(b.x)], 1u);
;         const unsigned gen = old / nloc;
;         if (old + 1u == (gen + 1u) * nloc) {
;             __builtin_amdgcn_fence(__ATOMIC_RELEASE, "agent");
;             asm volatile("s_waitcnt vmcnt(0)" ::: "memory");
;             const unsigned og = xb_add(&bar[XB_TOP], 1u);
;             const unsigned tg = og / nx;
;             if (og + 1u == (tg + 1u) * nx) xb_add(&bar[XB_TOPGEN], 1u);
;             else XB_SPIN(xb_ld(&bar[XB_TOPGEN]) == tg, bar);
.LBB0_140:
	s_waitcnt lgkmcnt(0)
	v_readfirstlane_b32 s98, v2
	v_readfirstlane_b32 s99, v0
	v_mov_b32_e32 v1, 0x20008
	ds_read_b32 v5, v1
	s_lshl_b32 s96, s59, 8
	s_add_u32 s96, s54, s96
	s_addc_u32 s97, s55, 0
	v_mov_b32_e32 v3, 0x1000
	v_mov_b32_e32 v4, 1
	global_atomic_add v3, v3, v4, s[96:97] offset:1024 sc0
	s_waitcnt lgkmcnt(0)
	v_readfirstlane_b32 s100, v5
	s_add_i32 s100, s100, 1
	v_mov_b32_e32 v2, s100
	ds_write_b32 v1, v2
	s_mul_i32 s98, s98, s100
	s_mul_i32 s99, s99, s100
	s_waitcnt vmcnt(0)
	v_readfirstlane_b32 s96, v3
	s_add_i32 s96, s96, 1
	s_cmp_lg_u32 s96, s98
	s_cbranch_scc0 .Lmy_bar_last_0
	s_sub_i32 s97, s98, s96
	s_cmp_lg_u32 s97, 8
	s_cbranch_scc1 .Lmy_bar_poll_0
	buffer_wbl2 sc1
	s_branch .Lmy_bar_poll_0
